# v27: FFN seams (GU->DOWN, EVOUT/ODOUT->GU, DOWN->next GU) use a 4-workgroup group barrier (row tile pm is owned by the same 4 WGs); payload stored write-through sc1, every wave drains, counter atomic,
# speedup vs baseline: 1.0199x; 1.0183x over previous
.LBB0_1614:
	s_waitcnt vmcnt(13)
	v_lshlrev_b32_e32 v164, 16, v196
	v_and_b32_e32 v165, 0xffff0000, v196
	v_lshlrev_b32_e32 v166, 16, v197
	v_and_b32_e32 v167, 0xffff0000, v197
	v_lshlrev_b32_e32 v168, 16, v198
	v_and_b32_e32 v169, 0xffff0000, v198
	v_lshlrev_b32_e32 v170, 16, v199
	v_and_b32_e32 v171, 0xffff0000, v199
	v_pk_fma_f32 v[122:123], v[148:149], v[122:123], v[164:165]
	v_pk_fma_f32 v[124:125], v[148:149], v[124:125], v[166:167]
	v_pk_fma_f32 v[126:127], v[148:149], v[126:127], v[168:169]
	v_pk_fma_f32 v[128:129], v[148:149], v[128:129], v[170:171]
	v_cvt_pk_bf16_f32 v196, v122, v123
	v_cvt_pk_bf16_f32 v197, v124, v125
	v_cvt_pk_bf16_f32 v198, v126, v127
	v_cvt_pk_bf16_f32 v199, v128, v129
	global_store_dwordx4 v[158:159], v[196:199], off sc1
	v_lshlrev_b32_e32 v122, 16, v196
	v_and_b32_e32 v123, 0xffff0000, v196
	v_lshlrev_b32_e32 v124, 16, v197
	v_and_b32_e32 v125, 0xffff0000, v197
	v_lshlrev_b32_e32 v126, 16, v198
	v_and_b32_e32 v127, 0xffff0000, v198
	v_lshlrev_b32_e32 v128, 16, v199
	v_and_b32_e32 v129, 0xffff0000, v199
	v_mul_f32_e32 v172, v123, v123
	v_fmac_f32_e32 v172, v122, v122
	v_fmac_f32_e32 v172, v124, v124
	v_fmac_f32_e32 v172, v125, v125
	v_fmac_f32_e32 v172, v126, v126
	v_fmac_f32_e32 v172, v127, v127
	v_fmac_f32_e32 v172, v128, v128
	v_fmac_f32_e32 v172, v129, v129
	s_waitcnt vmcnt(13)
	v_lshlrev_b32_e32 v164, 16, v200
	v_and_b32_e32 v165, 0xffff0000, v200
	v_lshlrev_b32_e32 v166, 16, v201
	v_and_b32_e32 v167, 0xffff0000, v201
	v_lshlrev_b32_e32 v168, 16, v202
	v_and_b32_e32 v169, 0xffff0000, v202
	v_lshlrev_b32_e32 v170, 16, v203
	v_and_b32_e32 v171, 0xffff0000, v203
	v_pk_fma_f32 v[118:119], v[148:149], v[118:119], v[164:165]
	v_pk_fma_f32 v[120:121], v[148:149], v[120:121], v[166:167]
	v_pk_fma_f32 v[114:115], v[148:149], v[114:115], v[168:169]
	v_pk_fma_f32 v[116:117], v[148:149], v[116:117], v[170:171]
	v_cvt_pk_bf16_f32 v200, v118, v119
	v_cvt_pk_bf16_f32 v201, v120, v121
	v_cvt_pk_bf16_f32 v202, v114, v115
	v_cvt_pk_bf16_f32 v203, v116, v117
	global_store_dwordx4 v[158:159], v[200:203], off offset:256 sc1
	v_lshlrev_b32_e32 v118, 16, v200
	v_and_b32_e32 v119, 0xffff0000, v200
	v_lshlrev_b32_e32 v120, 16, v201
	v_and_b32_e32 v121, 0xffff0000, v201
	v_lshlrev_b32_e32 v114, 16, v202
	v_and_b32_e32 v115, 0xffff0000, v202
	v_lshlrev_b32_e32 v116, 16, v203
	v_and_b32_e32 v117, 0xffff0000, v203
	v_fmac_f32_e32 v172, v118, v118
	v_fmac_f32_e32 v172, v119, v119
	v_fmac_f32_e32 v172, v120, v120
	v_fmac_f32_e32 v172, v121, v121
	v_fmac_f32_e32 v172, v114, v114
	v_fmac_f32_e32 v172, v115, v115
	v_fmac_f32_e32 v172, v116, v116
	v_fmac_f32_e32 v172, v117, v117
	global_load_dwordx4 v[114:117], v[154:155], off
	global_load_dwordx4 v[118:121], v[154:155], off offset:256
	s_waitcnt vmcnt(15)
	v_lshlrev_b32_e32 v164, 16, v204
	v_and_b32_e32 v165, 0xffff0000, v204
	v_lshlrev_b32_e32 v166, 16, v205
	v_and_b32_e32 v167, 0xffff0000, v205
	v_lshlrev_b32_e32 v168, 16, v206
	v_and_b32_e32 v169, 0xffff0000, v206
	v_lshlrev_b32_e32 v170, 16, v207
	v_and_b32_e32 v171, 0xffff0000, v207
	v_pk_fma_f32 v[110:111], v[148:149], v[110:111], v[164:165]
	v_pk_fma_f32 v[112:113], v[148:149], v[112:113], v[166:167]
	v_pk_fma_f32 v[106:107], v[148:149], v[106:107], v[168:169]
	v_pk_fma_f32 v[108:109], v[148:149], v[108:109], v[170:171]
	v_cvt_pk_bf16_f32 v204, v110, v111
	v_cvt_pk_bf16_f32 v205, v112, v113
	v_cvt_pk_bf16_f32 v206, v106, v107
	v_cvt_pk_bf16_f32 v207, v108, v109
	global_store_dwordx4 v[174:175], v[204:207], off sc1
	v_lshlrev_b32_e32 v110, 16, v204
	v_and_b32_e32 v111, 0xffff0000, v204
	v_lshlrev_b32_e32 v112, 16, v205
	v_and_b32_e32 v113, 0xffff0000, v205
	v_lshlrev_b32_e32 v106, 16, v206
	v_and_b32_e32 v107, 0xffff0000, v206
	v_lshlrev_b32_e32 v108, 16, v207
	v_and_b32_e32 v109, 0xffff0000, v207
	v_mul_f32_e32 v122, v111, v111
	v_fmac_f32_e32 v122, v110, v110
	v_fmac_f32_e32 v122, v112, v112
	v_fmac_f32_e32 v122, v113, v113
	v_fmac_f32_e32 v122, v106, v106
	v_fmac_f32_e32 v122, v107, v107
	v_fmac_f32_e32 v122, v108, v108
	v_fmac_f32_e32 v122, v109, v109
	s_waitcnt vmcnt(15)
	v_lshlrev_b32_e32 v164, 16, v208
	v_and_b32_e32 v165, 0xffff0000, v208
	v_lshlrev_b32_e32 v166, 16, v209
	v_and_b32_e32 v167, 0xffff0000, v209
	v_lshlrev_b32_e32 v168, 16, v210
	v_and_b32_e32 v169, 0xffff0000, v210
	v_lshlrev_b32_e32 v170, 16, v211
	v_and_b32_e32 v171, 0xffff0000, v211
	v_pk_fma_f32 v[102:103], v[148:149], v[102:103], v[164:165]
	v_pk_fma_f32 v[104:105], v[148:149], v[104:105], v[166:167]
	v_pk_fma_f32 v[98:99], v[148:149], v[98:99], v[168:169]
	v_pk_fma_f32 v[100:101], v[148:149], v[100:101], v[170:171]
	v_cvt_pk_bf16_f32 v208, v102, v103
	v_cvt_pk_bf16_f32 v209, v104, v105
	v_cvt_pk_bf16_f32 v210, v98, v99
	v_cvt_pk_bf16_f32 v211, v100, v101
	global_store_dwordx4 v[174:175], v[208:211], off offset:256 sc1
	v_lshlrev_b32_e32 v102, 16, v208
	v_and_b32_e32 v103, 0xffff0000, v208
	v_lshlrev_b32_e32 v104, 16, v209
	v_and_b32_e32 v105, 0xffff0000, v209
	v_lshlrev_b32_e32 v98, 16, v210
	v_and_b32_e32 v99, 0xffff0000, v210
	v_lshlrev_b32_e32 v100, 16, v211
	v_and_b32_e32 v101, 0xffff0000, v211
	v_fmac_f32_e32 v122, v102, v102
	v_fmac_f32_e32 v122, v103, v103
	v_fmac_f32_e32 v122, v104, v104
	v_fmac_f32_e32 v122, v105, v105
	v_fmac_f32_e32 v122, v98, v98
	v_fmac_f32_e32 v122, v99, v99
	v_fmac_f32_e32 v122, v100, v100
	v_fmac_f32_e32 v122, v101, v101
	s_waitcnt vmcnt(15)
	v_lshlrev_b32_e32 v164, 16, v212
	v_and_b32_e32 v165, 0xffff0000, v212
	v_lshlrev_b32_e32 v166, 16, v213
	v_and_b32_e32 v167, 0xffff0000, v213
	v_lshlrev_b32_e32 v168, 16, v214
	v_and_b32_e32 v169, 0xffff0000, v214
	v_lshlrev_b32_e32 v170, 16, v215
	v_and_b32_e32 v171, 0xffff0000, v215
	v_pk_fma_f32 v[94:95], v[148:149], v[94:95], v[164:165]
	v_pk_fma_f32 v[96:97], v[148:149], v[96:97], v[166:167]
	v_pk_fma_f32 v[90:91], v[148:149], v[90:91], v[168:169]
	v_pk_fma_f32 v[92:93], v[148:149], v[92:93], v[170:171]
	v_cvt_pk_bf16_f32 v212, v94, v95
	v_cvt_pk_bf16_f32 v213, v96, v97
	v_cvt_pk_bf16_f32 v214, v90, v91
	v_cvt_pk_bf16_f32 v215, v92, v93
	global_store_dwordx4 v[176:177], v[212:215], off sc1
	v_lshlrev_b32_e32 v94, 16, v212
	v_and_b32_e32 v95, 0xffff0000, v212
	v_lshlrev_b32_e32 v96, 16, v213
	v_and_b32_e32 v97, 0xffff0000, v213
	v_lshlrev_b32_e32 v90, 16, v214
	v_and_b32_e32 v91, 0xffff0000, v214
	v_lshlrev_b32_e32 v92, 16, v215
	v_and_b32_e32 v93, 0xffff0000, v215
	v_mul_f32_e32 v123, v95, v95
	v_fmac_f32_e32 v123, v94, v94
	v_fmac_f32_e32 v123, v96, v96
	v_fmac_f32_e32 v123, v97, v97
	v_fmac_f32_e32 v123, v90, v90
	v_fmac_f32_e32 v123, v91, v91
	v_fmac_f32_e32 v123, v92, v92
	v_fmac_f32_e32 v123, v93, v93
	s_waitcnt vmcnt(15)
	v_lshlrev_b32_e32 v164, 16, v216
	v_and_b32_e32 v165, 0xffff0000, v216
	v_lshlrev_b32_e32 v166, 16, v217
	v_and_b32_e32 v167, 0xffff0000, v217
	v_lshlrev_b32_e32 v168, 16, v218
	v_and_b32_e32 v169, 0xffff0000, v218
	v_lshlrev_b32_e32 v170, 16, v219
	v_and_b32_e32 v171, 0xffff0000, v219
	v_pk_fma_f32 v[86:87], v[148:149], v[86:87], v[164:165]
	v_pk_fma_f32 v[88:89], v[148:149], v[88:89], v[166:167]
	v_pk_fma_f32 v[82:83], v[148:149], v[82:83], v[168:169]
	v_pk_fma_f32 v[84:85], v[148:149], v[84:85], v[170:171]
	v_cvt_pk_bf16_f32 v216, v86, v87
	v_cvt_pk_bf16_f32 v217, v88, v89
	v_cvt_pk_bf16_f32 v218, v82, v83
	v_cvt_pk_bf16_f32 v219, v84, v85
	global_store_dwordx4 v[176:177], v[216:219], off offset:256 sc1
	v_lshlrev_b32_e32 v86, 16, v216
	v_and_b32_e32 v87, 0xffff0000, v216
	v_lshlrev_b32_e32 v88, 16, v217
	v_and_b32_e32 v89, 0xffff0000, v217
	v_lshlrev_b32_e32 v82, 16, v218
	v_and_b32_e32 v83, 0xffff0000, v218
	v_lshlrev_b32_e32 v84, 16, v219
	v_and_b32_e32 v85, 0xffff0000, v219
	v_fmac_f32_e32 v123, v86, v86
	v_fmac_f32_e32 v123, v87, v87
	v_fmac_f32_e32 v123, v88, v88
	v_fmac_f32_e32 v123, v89, v89
	v_fmac_f32_e32 v123, v82, v82
	v_fmac_f32_e32 v123, v83, v83
	v_fmac_f32_e32 v123, v84, v84
	v_fmac_f32_e32 v123, v85, v85
	s_waitcnt vmcnt(15)
	v_lshlrev_b32_e32 v164, 16, v220
	v_and_b32_e32 v165, 0xffff0000, v220
	v_lshlrev_b32_e32 v166, 16, v221
	v_and_b32_e32 v167, 0xffff0000, v221
	v_lshlrev_b32_e32 v168, 16, v222
	v_and_b32_e32 v169, 0xffff0000, v222
	v_lshlrev_b32_e32 v170, 16, v223
	v_and_b32_e32 v171, 0xffff0000, v223
	v_pk_fma_f32 v[78:79], v[148:149], v[78:79], v[164:165]
	v_pk_fma_f32 v[80:81], v[148:149], v[80:81], v[166:167]
	v_pk_fma_f32 v[74:75], v[148:149], v[74:75], v[168:169]
	v_pk_fma_f32 v[76:77], v[148:149], v[76:77], v[170:171]
	v_cvt_pk_bf16_f32 v220, v78, v79
	v_cvt_pk_bf16_f32 v221, v80, v81
	v_cvt_pk_bf16_f32 v222, v74, v75
	v_cvt_pk_bf16_f32 v223, v76, v77
	global_store_dwordx4 v[178:179], v[220:223], off sc1
	v_lshlrev_b32_e32 v78, 16, v220
	v_and_b32_e32 v79, 0xffff0000, v220
	v_lshlrev_b32_e32 v80, 16, v221
	v_and_b32_e32 v81, 0xffff0000, v221
	v_lshlrev_b32_e32 v74, 16, v222
	v_and_b32_e32 v75, 0xffff0000, v222
	v_lshlrev_b32_e32 v76, 16, v223
	v_and_b32_e32 v77, 0xffff0000, v223
	v_mul_f32_e32 v124, v79, v79
	v_fmac_f32_e32 v124, v78, v78
	v_fmac_f32_e32 v124, v80, v80
	v_fmac_f32_e32 v124, v81, v81
	v_fmac_f32_e32 v124, v74, v74
	v_fmac_f32_e32 v124, v75, v75
	v_fmac_f32_e32 v124, v76, v76
	v_fmac_f32_e32 v124, v77, v77
	s_waitcnt vmcnt(15)
	v_lshlrev_b32_e32 v164, 16, v224
	v_and_b32_e32 v165, 0xffff0000, v224
	v_lshlrev_b32_e32 v166, 16, v225
	v_and_b32_e32 v167, 0xffff0000, v225
	v_lshlrev_b32_e32 v168, 16, v226
	v_and_b32_e32 v169, 0xffff0000, v226
	v_lshlrev_b32_e32 v170, 16, v227
	v_and_b32_e32 v171, 0xffff0000, v227
	v_pk_fma_f32 v[70:71], v[148:149], v[70:71], v[164:165]
	v_pk_fma_f32 v[72:73], v[148:149], v[72:73], v[166:167]
	v_pk_fma_f32 v[66:67], v[148:149], v[66:67], v[168:169]
	v_pk_fma_f32 v[68:69], v[148:149], v[68:69], v[170:171]
	v_cvt_pk_bf16_f32 v224, v70, v71
	v_cvt_pk_bf16_f32 v225, v72, v73
	v_cvt_pk_bf16_f32 v226, v66, v67
	v_cvt_pk_bf16_f32 v227, v68, v69
	global_store_dwordx4 v[178:179], v[224:227], off offset:256 sc1
	v_lshlrev_b32_e32 v70, 16, v224
	v_and_b32_e32 v71, 0xffff0000, v224
	v_lshlrev_b32_e32 v72, 16, v225
	v_and_b32_e32 v73, 0xffff0000, v225
	v_lshlrev_b32_e32 v66, 16, v226
	v_and_b32_e32 v67, 0xffff0000, v226
	v_lshlrev_b32_e32 v68, 16, v227
	v_and_b32_e32 v69, 0xffff0000, v227
	v_fmac_f32_e32 v124, v70, v70
	v_fmac_f32_e32 v124, v71, v71
	v_fmac_f32_e32 v124, v72, v72
	v_fmac_f32_e32 v124, v73, v73
	v_fmac_f32_e32 v124, v66, v66
	v_fmac_f32_e32 v124, v67, v67
	v_fmac_f32_e32 v124, v68, v68
	v_fmac_f32_e32 v124, v69, v69
	s_waitcnt vmcnt(15)
	v_lshlrev_b32_e32 v164, 16, v228
	v_and_b32_e32 v165, 0xffff0000, v228
	v_lshlrev_b32_e32 v166, 16, v229
	v_and_b32_e32 v167, 0xffff0000, v229
	v_lshlrev_b32_e32 v168, 16, v230
	v_and_b32_e32 v169, 0xffff0000, v230
	v_lshlrev_b32_e32 v170, 16, v231
	v_and_b32_e32 v171, 0xffff0000, v231
	v_pk_fma_f32 v[62:63], v[148:149], v[62:63], v[164:165]
	v_pk_fma_f32 v[64:65], v[148:149], v[64:65], v[166:167]
	v_pk_fma_f32 v[58:59], v[148:149], v[58:59], v[168:169]
	v_pk_fma_f32 v[60:61], v[148:149], v[60:61], v[170:171]
	v_cvt_pk_bf16_f32 v228, v62, v63
	v_cvt_pk_bf16_f32 v229, v64, v65
	v_cvt_pk_bf16_f32 v230, v58, v59
	v_cvt_pk_bf16_f32 v231, v60, v61
	global_store_dwordx4 v[180:181], v[228:231], off sc1
	v_lshlrev_b32_e32 v62, 16, v228
	v_and_b32_e32 v63, 0xffff0000, v228
	v_lshlrev_b32_e32 v64, 16, v229
	v_and_b32_e32 v65, 0xffff0000, v229
	v_lshlrev_b32_e32 v58, 16, v230
	v_and_b32_e32 v59, 0xffff0000, v230
	v_lshlrev_b32_e32 v60, 16, v231
	v_and_b32_e32 v61, 0xffff0000, v231
	v_mul_f32_e32 v125, v63, v63
	v_fmac_f32_e32 v125, v62, v62
	v_fmac_f32_e32 v125, v64, v64
	v_fmac_f32_e32 v125, v65, v65
	v_fmac_f32_e32 v125, v58, v58
	v_fmac_f32_e32 v125, v59, v59
	v_fmac_f32_e32 v125, v60, v60
	v_fmac_f32_e32 v125, v61, v61
	s_waitcnt vmcnt(15)
	v_lshlrev_b32_e32 v164, 16, v232
	v_and_b32_e32 v165, 0xffff0000, v232
	v_lshlrev_b32_e32 v166, 16, v233
	v_and_b32_e32 v167, 0xffff0000, v233
	v_lshlrev_b32_e32 v168, 16, v234
	v_and_b32_e32 v169, 0xffff0000, v234
	v_lshlrev_b32_e32 v170, 16, v235
	v_and_b32_e32 v171, 0xffff0000, v235
	v_pk_fma_f32 v[54:55], v[148:149], v[54:55], v[164:165]
	v_pk_fma_f32 v[56:57], v[148:149], v[56:57], v[166:167]
	v_pk_fma_f32 v[50:51], v[148:149], v[50:51], v[168:169]
	v_pk_fma_f32 v[52:53], v[148:149], v[52:53], v[170:171]
	v_cvt_pk_bf16_f32 v232, v54, v55
	v_cvt_pk_bf16_f32 v233, v56, v57
	v_cvt_pk_bf16_f32 v234, v50, v51
	v_cvt_pk_bf16_f32 v235, v52, v53
	global_store_dwordx4 v[180:181], v[232:235], off offset:256 sc1
	v_lshlrev_b32_e32 v54, 16, v232
	v_and_b32_e32 v55, 0xffff0000, v232
	v_lshlrev_b32_e32 v56, 16, v233
	v_and_b32_e32 v57, 0xffff0000, v233
	v_lshlrev_b32_e32 v50, 16, v234
	v_and_b32_e32 v51, 0xffff0000, v234
	v_lshlrev_b32_e32 v52, 16, v235
	v_and_b32_e32 v53, 0xffff0000, v235
	v_fmac_f32_e32 v125, v54, v54
	v_fmac_f32_e32 v125, v55, v55
	v_fmac_f32_e32 v125, v56, v56
	v_fmac_f32_e32 v125, v57, v57
	v_fmac_f32_e32 v125, v50, v50
	v_fmac_f32_e32 v125, v51, v51
	v_fmac_f32_e32 v125, v52, v52
	v_fmac_f32_e32 v125, v53, v53
	s_waitcnt vmcnt(15)
	v_lshlrev_b32_e32 v164, 16, v236
	v_and_b32_e32 v165, 0xffff0000, v236
	v_lshlrev_b32_e32 v166, 16, v237
	v_and_b32_e32 v167, 0xffff0000, v237
	v_lshlrev_b32_e32 v168, 16, v238
	v_and_b32_e32 v169, 0xffff0000, v238
	v_lshlrev_b32_e32 v170, 16, v239
	v_and_b32_e32 v171, 0xffff0000, v239
	v_pk_fma_f32 v[46:47], v[148:149], v[46:47], v[164:165]
	v_pk_fma_f32 v[48:49], v[148:149], v[48:49], v[166:167]
	v_pk_fma_f32 v[42:43], v[148:149], v[42:43], v[168:169]
	v_pk_fma_f32 v[44:45], v[148:149], v[44:45], v[170:171]
	v_cvt_pk_bf16_f32 v236, v46, v47
	v_cvt_pk_bf16_f32 v237, v48, v49
	v_cvt_pk_bf16_f32 v238, v42, v43
	v_cvt_pk_bf16_f32 v239, v44, v45
	global_store_dwordx4 v[182:183], v[236:239], off sc1
	v_lshlrev_b32_e32 v46, 16, v236
	v_and_b32_e32 v47, 0xffff0000, v236
	v_lshlrev_b32_e32 v48, 16, v237
	v_and_b32_e32 v49, 0xffff0000, v237
	v_lshlrev_b32_e32 v42, 16, v238
	v_and_b32_e32 v43, 0xffff0000, v238
	v_lshlrev_b32_e32 v44, 16, v239
	v_and_b32_e32 v45, 0xffff0000, v239
	v_mul_f32_e32 v126, v47, v47
	v_fmac_f32_e32 v126, v46, v46
	v_fmac_f32_e32 v126, v48, v48
	v_fmac_f32_e32 v126, v49, v49
	v_fmac_f32_e32 v126, v42, v42
	v_fmac_f32_e32 v126, v43, v43
	v_fmac_f32_e32 v126, v44, v44
	v_fmac_f32_e32 v126, v45, v45
	s_waitcnt vmcnt(15)
	v_lshlrev_b32_e32 v164, 16, v240
	v_and_b32_e32 v165, 0xffff0000, v240
	v_lshlrev_b32_e32 v166, 16, v241
	v_and_b32_e32 v167, 0xffff0000, v241
	v_lshlrev_b32_e32 v168, 16, v242
	v_and_b32_e32 v169, 0xffff0000, v242
	v_lshlrev_b32_e32 v170, 16, v243
	v_and_b32_e32 v171, 0xffff0000, v243
	v_pk_fma_f32 v[38:39], v[148:149], v[38:39], v[164:165]
	v_pk_fma_f32 v[40:41], v[148:149], v[40:41], v[166:167]
	v_pk_fma_f32 v[34:35], v[148:149], v[34:35], v[168:169]
	v_pk_fma_f32 v[36:37], v[148:149], v[36:37], v[170:171]
	v_cvt_pk_bf16_f32 v240, v38, v39
	v_cvt_pk_bf16_f32 v241, v40, v41
	v_cvt_pk_bf16_f32 v242, v34, v35
	v_cvt_pk_bf16_f32 v243, v36, v37
	global_store_dwordx4 v[182:183], v[240:243], off offset:256 sc1
	v_lshlrev_b32_e32 v38, 16, v240
	v_and_b32_e32 v39, 0xffff0000, v240
	v_lshlrev_b32_e32 v40, 16, v241
	v_and_b32_e32 v41, 0xffff0000, v241
	v_lshlrev_b32_e32 v34, 16, v242
	v_and_b32_e32 v35, 0xffff0000, v242
	v_lshlrev_b32_e32 v36, 16, v243
	v_and_b32_e32 v37, 0xffff0000, v243
	v_fmac_f32_e32 v126, v38, v38
	v_fmac_f32_e32 v126, v39, v39
	v_fmac_f32_e32 v126, v40, v40
	v_fmac_f32_e32 v126, v41, v41
	v_fmac_f32_e32 v126, v34, v34
	v_fmac_f32_e32 v126, v35, v35
	v_fmac_f32_e32 v126, v36, v36
	v_fmac_f32_e32 v126, v37, v37
	s_waitcnt vmcnt(15)
	v_lshlrev_b32_e32 v164, 16, v244
	v_and_b32_e32 v165, 0xffff0000, v244
	v_lshlrev_b32_e32 v166, 16, v245
	v_and_b32_e32 v167, 0xffff0000, v245
	v_lshlrev_b32_e32 v168, 16, v246
	v_and_b32_e32 v169, 0xffff0000, v246
	v_lshlrev_b32_e32 v170, 16, v247
	v_and_b32_e32 v171, 0xffff0000, v247
	v_pk_fma_f32 v[30:31], v[148:149], v[30:31], v[164:165]
	v_pk_fma_f32 v[32:33], v[148:149], v[32:33], v[166:167]
	v_pk_fma_f32 v[26:27], v[148:149], v[26:27], v[168:169]
	v_pk_fma_f32 v[28:29], v[148:149], v[28:29], v[170:171]
	v_cvt_pk_bf16_f32 v244, v30, v31
	v_cvt_pk_bf16_f32 v245, v32, v33
	v_cvt_pk_bf16_f32 v246, v26, v27
	v_cvt_pk_bf16_f32 v247, v28, v29
	global_store_dwordx4 v[252:253], v[244:247], off sc1
	v_lshlrev_b32_e32 v30, 16, v244
	v_and_b32_e32 v31, 0xffff0000, v244
	v_lshlrev_b32_e32 v32, 16, v245
	v_and_b32_e32 v33, 0xffff0000, v245
	v_lshlrev_b32_e32 v26, 16, v246
	v_and_b32_e32 v27, 0xffff0000, v246
	v_lshlrev_b32_e32 v28, 16, v247
	v_and_b32_e32 v29, 0xffff0000, v247
	v_mul_f32_e32 v127, v31, v31
	v_fmac_f32_e32 v127, v30, v30
	v_fmac_f32_e32 v127, v32, v32
	v_fmac_f32_e32 v127, v33, v33
	v_fmac_f32_e32 v127, v26, v26
	v_fmac_f32_e32 v127, v27, v27
	v_fmac_f32_e32 v127, v28, v28
	v_fmac_f32_e32 v127, v29, v29
	s_waitcnt vmcnt(15)
	v_lshlrev_b32_e32 v164, 16, v248
	v_and_b32_e32 v165, 0xffff0000, v248
	v_lshlrev_b32_e32 v166, 16, v249
	v_and_b32_e32 v167, 0xffff0000, v249
	v_lshlrev_b32_e32 v168, 16, v250
	v_and_b32_e32 v169, 0xffff0000, v250
	v_lshlrev_b32_e32 v170, 16, v251
	v_and_b32_e32 v171, 0xffff0000, v251
	v_pk_fma_f32 v[22:23], v[148:149], v[22:23], v[164:165]
	v_pk_fma_f32 v[24:25], v[148:149], v[24:25], v[166:167]
	v_pk_fma_f32 v[18:19], v[148:149], v[18:19], v[168:169]
	v_pk_fma_f32 v[20:21], v[148:149], v[20:21], v[170:171]
	v_cvt_pk_bf16_f32 v248, v22, v23
	v_cvt_pk_bf16_f32 v249, v24, v25
	v_cvt_pk_bf16_f32 v250, v18, v19
	v_cvt_pk_bf16_f32 v251, v20, v21
	global_store_dwordx4 v[252:253], v[248:251], off offset:256 sc1
	v_lshlrev_b32_e32 v22, 16, v248
	v_and_b32_e32 v23, 0xffff0000, v248
	v_lshlrev_b32_e32 v24, 16, v249
	v_and_b32_e32 v25, 0xffff0000, v249
	v_lshlrev_b32_e32 v18, 16, v250
	v_and_b32_e32 v19, 0xffff0000, v250
	v_lshlrev_b32_e32 v20, 16, v251
	v_and_b32_e32 v21, 0xffff0000, v251
	v_fmac_f32_e32 v127, v22, v22
	v_fmac_f32_e32 v127, v23, v23
	v_fmac_f32_e32 v127, v24, v24
	v_fmac_f32_e32 v127, v25, v25
	v_fmac_f32_e32 v127, v18, v18
	v_fmac_f32_e32 v127, v19, v19
	v_fmac_f32_e32 v127, v20, v20
	v_fmac_f32_e32 v127, v21, v21
	s_waitcnt vmcnt(13)
	v_lshlrev_b32_e32 v164, 16, v114
	v_and_b32_e32 v165, 0xffff0000, v114
	v_lshlrev_b32_e32 v166, 16, v115
	v_and_b32_e32 v167, 0xffff0000, v115
	v_lshlrev_b32_e32 v168, 16, v116
	v_and_b32_e32 v169, 0xffff0000, v116
	v_lshlrev_b32_e32 v170, 16, v117
	v_and_b32_e32 v171, 0xffff0000, v117
	v_pk_fma_f32 v[14:15], v[148:149], v[14:15], v[164:165]
	v_pk_fma_f32 v[16:17], v[148:149], v[16:17], v[166:167]
	v_pk_fma_f32 v[10:11], v[148:149], v[10:11], v[168:169]
	v_pk_fma_f32 v[12:13], v[148:149], v[12:13], v[170:171]
	v_cvt_pk_bf16_f32 v114, v14, v15
	v_cvt_pk_bf16_f32 v115, v16, v17
	v_cvt_pk_bf16_f32 v116, v10, v11
	v_cvt_pk_bf16_f32 v117, v12, v13
	global_store_dwordx4 v[154:155], v[114:117], off sc1
	v_lshlrev_b32_e32 v14, 16, v114
	v_and_b32_e32 v15, 0xffff0000, v114
	v_lshlrev_b32_e32 v16, 16, v115
	v_and_b32_e32 v17, 0xffff0000, v115
	v_lshlrev_b32_e32 v10, 16, v116
	v_and_b32_e32 v11, 0xffff0000, v116
	v_lshlrev_b32_e32 v12, 16, v117
	v_and_b32_e32 v13, 0xffff0000, v117
	v_mul_f32_e32 v128, v15, v15
	v_fmac_f32_e32 v128, v14, v14
	v_fmac_f32_e32 v128, v16, v16
	v_fmac_f32_e32 v128, v17, v17
	v_fmac_f32_e32 v128, v10, v10
	v_fmac_f32_e32 v128, v11, v11
	v_fmac_f32_e32 v128, v12, v12
	v_fmac_f32_e32 v128, v13, v13
	s_waitcnt vmcnt(13)
	v_lshlrev_b32_e32 v164, 16, v118
	v_and_b32_e32 v165, 0xffff0000, v118
	v_lshlrev_b32_e32 v166, 16, v119
	v_and_b32_e32 v167, 0xffff0000, v119
	v_lshlrev_b32_e32 v168, 16, v120
	v_and_b32_e32 v169, 0xffff0000, v120
	v_lshlrev_b32_e32 v170, 16, v121
	v_and_b32_e32 v171, 0xffff0000, v121
	v_pk_fma_f32 v[6:7], v[148:149], v[6:7], v[164:165]
	v_pk_fma_f32 v[8:9], v[148:149], v[8:9], v[166:167]
	v_pk_fma_f32 v[2:3], v[148:149], v[2:3], v[168:169]
	v_pk_fma_f32 v[4:5], v[148:149], v[4:5], v[170:171]
	v_cvt_pk_bf16_f32 v118, v6, v7
	v_cvt_pk_bf16_f32 v119, v8, v9
	v_cvt_pk_bf16_f32 v120, v2, v3
	v_cvt_pk_bf16_f32 v121, v4, v5
	global_store_dwordx4 v[154:155], v[118:121], off offset:256 sc1
	v_lshlrev_b32_e32 v6, 16, v118
	v_and_b32_e32 v7, 0xffff0000, v118
	v_lshlrev_b32_e32 v8, 16, v119
	v_and_b32_e32 v9, 0xffff0000, v119
	v_lshlrev_b32_e32 v2, 16, v120
	v_and_b32_e32 v3, 0xffff0000, v120
	v_lshlrev_b32_e32 v4, 16, v121
	v_and_b32_e32 v5, 0xffff0000, v121
	v_fmac_f32_e32 v128, v6, v6
	v_fmac_f32_e32 v128, v7, v7
	v_fmac_f32_e32 v128, v8, v8
	v_fmac_f32_e32 v128, v9, v9
	v_fmac_f32_e32 v128, v2, v2
	v_fmac_f32_e32 v128, v3, v3
	v_fmac_f32_e32 v128, v4, v4
	v_fmac_f32_e32 v128, v5, v5
	v_xor_b32_e32 v106, 16, v189
	v_xor_b32_e32 v107, 32, v189
	v_lshlrev_b32_e32 v106, 2, v106
	v_lshlrev_b32_e32 v107, 2, v107
	ds_bpermute_b32 v98, v106, v172
	ds_bpermute_b32 v99, v106, v122
	ds_bpermute_b32 v100, v106, v123
	ds_bpermute_b32 v101, v106, v124
	ds_bpermute_b32 v102, v106, v125
	ds_bpermute_b32 v103, v106, v126
	ds_bpermute_b32 v104, v106, v127
	ds_bpermute_b32 v105, v106, v128
	s_waitcnt lgkmcnt(0)
	v_add_f32_e32 v172, v172, v98
	v_add_f32_e32 v122, v122, v99
	v_add_f32_e32 v123, v123, v100
	v_add_f32_e32 v124, v124, v101
	v_add_f32_e32 v125, v125, v102
	v_add_f32_e32 v126, v126, v103
	v_add_f32_e32 v127, v127, v104
	v_add_f32_e32 v128, v128, v105
	ds_bpermute_b32 v98, v107, v172
	ds_bpermute_b32 v99, v107, v122
	ds_bpermute_b32 v100, v107, v123
	ds_bpermute_b32 v101, v107, v124
	ds_bpermute_b32 v102, v107, v125
	ds_bpermute_b32 v103, v107, v126
	ds_bpermute_b32 v104, v107, v127
	ds_bpermute_b32 v105, v107, v128
	s_lshl_b32 s0, s33, 2
	s_ashr_i32 s1, s0, 31
	s_lshl_b32 s54, s35, 2
	v_lshlrev_b64 v[108:109], 6, v[156:157]
	v_lshl_add_u64 v[108:109], s[72:73], 0, v[108:109]
	v_lshl_add_u64 v[108:109], s[0:1], 2, v[108:109]
	v_lshl_add_u64 v[108:109], v[108:109], 0, s[54:55]
	s_mov_b64 s[0:1], 0x2000
	v_lshl_add_u64 v[110:111], v[108:109], 0, s[0:1]
	s_waitcnt lgkmcnt(0)
	v_add_f32_e32 v172, v172, v98
	v_add_f32_e32 v122, v122, v99
	v_add_f32_e32 v123, v123, v100
	v_add_f32_e32 v124, v124, v101
	v_add_f32_e32 v125, v125, v102
	v_add_f32_e32 v126, v126, v103
	v_add_f32_e32 v127, v127, v104
	v_add_f32_e32 v128, v128, v105
	s_and_saveexec_b64 s[20:21], s[2:3]
	s_cbranch_execz .Lresid_ss_done
	global_store_dword v[108:109], v172, off sc1
	global_store_dword v[108:109], v122, off offset:1024 sc1
	global_store_dword v[108:109], v123, off offset:2048 sc1
	global_store_dword v[108:109], v124, off offset:3072 sc1
	global_store_dword v[110:111], v125, off sc1
	global_store_dword v[110:111], v126, off offset:1024 sc1
	global_store_dword v[110:111], v127, off offset:2048 sc1
	global_store_dword v[110:111], v128, off offset:3072 sc1

.LBB0_1653:
	v_mov_b64_e32 v[248:249], s[50:51]
	s_lshl_b32 s18, s33, 7
	s_ashr_i32 s19, s18, 31
	s_lshl_b64 s[18:19], s[18:19], 1
	v_lshl_add_u64 v[248:249], v[248:249], 0, s[18:19]
	v_lshl_add_u64 v[248:249], v[248:249], 0, s[54:55]
	v_lshl_add_u64 v[248:249], v[248:249], 0, v[0:1]
	s_waitcnt vmcnt(12)
	v_add_f32_e32 v154, v208, v209
	v_add_f32_e32 v155, v210, v211
	v_add_f32_e32 v154, v154, v155
	v_add_f32_e32 v155, v204, v205
	v_add_f32_e32 v182, v206, v207
	v_add_f32_e32 v155, v155, v182
	v_add_f32_e32 v154, v154, v155
	v_add_f32_e32 v155, v200, v201
	v_add_f32_e32 v182, v202, v203
	v_add_f32_e32 v155, v155, v182
	v_add_f32_e32 v154, v154, v155
	v_add_f32_e32 v155, v196, v197
	v_add_f32_e32 v182, v198, v199
	v_add_f32_e32 v155, v155, v182
	v_add_f32_e32 v154, v154, v155
	v_fmamk_f32 v154, v154, 0x3a800000, v184
	v_rsq_f32_e32 v154, v154
	global_load_dwordx4 v[196:199], v[246:247], off offset:48
	global_load_dwordx4 v[200:203], v[246:247], off offset:32
	global_load_dwordx4 v[204:207], v[246:247], off offset:16
	global_load_dwordx4 v[208:211], v[246:247], off
	v_pk_mul_f32 v[126:127], v[126:127], v[122:123]
	v_pk_mul_f32 v[128:129], v[128:129], v[124:125]
	v_mul_f32_e32 v158, 0xbfb8aa3b, v154
	v_mul_f32_e32 v156, v154, v154
	v_pk_mul_f32 v[118:119], v[118:119], v[114:115]
	v_pk_mul_f32 v[120:121], v[120:121], v[116:117]
	v_pk_mul_f32 v[122:123], v[122:123], v[158:159] op_sel_hi:[1,0]
	v_pk_mul_f32 v[124:125], v[124:125], v[158:159] op_sel_hi:[1,0]
	v_pk_mul_f32 v[114:115], v[114:115], v[158:159] op_sel_hi:[1,0]
	v_pk_mul_f32 v[116:117], v[116:117], v[158:159] op_sel_hi:[1,0]
	v_exp_f32_e32 v122, v122
	v_exp_f32_e32 v123, v123
	v_exp_f32_e32 v124, v124
	v_exp_f32_e32 v125, v125
	v_exp_f32_e32 v114, v114
	v_exp_f32_e32 v115, v115
	v_exp_f32_e32 v116, v116
	v_exp_f32_e32 v117, v117
	v_pk_add_f32 v[122:123], v[122:123], 1.0 op_sel_hi:[1,0]
	v_pk_add_f32 v[124:125], v[124:125], 1.0 op_sel_hi:[1,0]
	v_pk_add_f32 v[114:115], v[114:115], 1.0 op_sel_hi:[1,0]
	v_pk_add_f32 v[116:117], v[116:117], 1.0 op_sel_hi:[1,0]
	v_rcp_f32_e32 v122, v122
	v_rcp_f32_e32 v123, v123
	v_rcp_f32_e32 v124, v124
	v_rcp_f32_e32 v125, v125
	v_rcp_f32_e32 v114, v114
	v_rcp_f32_e32 v115, v115
	v_rcp_f32_e32 v116, v116
	v_rcp_f32_e32 v117, v117
	v_mad_i64_i32 v[250:251], s[0:1], v252, s56, v[248:249]
	v_pk_mul_f32 v[122:123], v[156:157], v[122:123] op_sel_hi:[0,1]
	v_pk_mul_f32 v[124:125], v[156:157], v[124:125] op_sel_hi:[0,1]
	v_pk_mul_f32 v[114:115], v[156:157], v[114:115] op_sel_hi:[0,1]
	v_pk_mul_f32 v[116:117], v[156:157], v[116:117] op_sel_hi:[0,1]
	v_pk_mul_f32 v[126:127], v[126:127], v[122:123]
	v_pk_mul_f32 v[128:129], v[128:129], v[124:125]
	v_pk_mul_f32 v[118:119], v[118:119], v[114:115]
	v_pk_mul_f32 v[120:121], v[120:121], v[116:117]
	v_cvt_pk_bf16_f32 v122, v126, v127
	v_cvt_pk_bf16_f32 v123, v128, v129
	v_cvt_pk_bf16_f32 v124, v118, v119
	v_cvt_pk_bf16_f32 v125, v120, v121
	global_store_dwordx4 v[250:251], v[122:125], off sc1
	s_waitcnt vmcnt(13)
	v_add_f32_e32 v154, v224, v225
	v_add_f32_e32 v155, v226, v227
	v_add_f32_e32 v154, v154, v155
	v_add_f32_e32 v155, v220, v221
	v_add_f32_e32 v182, v222, v223
	v_add_f32_e32 v155, v155, v182
	v_add_f32_e32 v154, v154, v155
	v_add_f32_e32 v155, v216, v217
	v_add_f32_e32 v182, v218, v219
	v_add_f32_e32 v155, v155, v182
	v_add_f32_e32 v154, v154, v155
	v_add_f32_e32 v155, v212, v213
	v_add_f32_e32 v182, v214, v215
	v_add_f32_e32 v155, v155, v182
	v_add_f32_e32 v154, v154, v155
	v_fmamk_f32 v154, v154, 0x3a800000, v184
	v_rsq_f32_e32 v154, v154
	global_load_dwordx4 v[212:215], v[246:247], off offset:1072
	global_load_dwordx4 v[216:219], v[246:247], off offset:1056
	global_load_dwordx4 v[220:223], v[246:247], off offset:1040
	global_load_dwordx4 v[224:227], v[246:247], off offset:1024
	v_pk_mul_f32 v[110:111], v[110:111], v[106:107]
	v_pk_mul_f32 v[112:113], v[112:113], v[108:109]
	v_mul_f32_e32 v158, 0xbfb8aa3b, v154
	v_mul_f32_e32 v156, v154, v154
	v_pk_mul_f32 v[102:103], v[102:103], v[98:99]
	v_pk_mul_f32 v[104:105], v[104:105], v[100:101]
	v_pk_mul_f32 v[106:107], v[106:107], v[158:159] op_sel_hi:[1,0]
	v_pk_mul_f32 v[108:109], v[108:109], v[158:159] op_sel_hi:[1,0]
	v_pk_mul_f32 v[98:99], v[98:99], v[158:159] op_sel_hi:[1,0]
	v_pk_mul_f32 v[100:101], v[100:101], v[158:159] op_sel_hi:[1,0]
	v_exp_f32_e32 v106, v106
	v_exp_f32_e32 v107, v107
	v_exp_f32_e32 v108, v108
	v_exp_f32_e32 v109, v109
	v_exp_f32_e32 v98, v98
	v_exp_f32_e32 v99, v99
	v_exp_f32_e32 v100, v100
	v_exp_f32_e32 v101, v101
	v_pk_add_f32 v[106:107], v[106:107], 1.0 op_sel_hi:[1,0]
	v_pk_add_f32 v[108:109], v[108:109], 1.0 op_sel_hi:[1,0]
	v_pk_add_f32 v[98:99], v[98:99], 1.0 op_sel_hi:[1,0]
	v_pk_add_f32 v[100:101], v[100:101], 1.0 op_sel_hi:[1,0]
	v_rcp_f32_e32 v106, v106
	v_rcp_f32_e32 v107, v107
	v_rcp_f32_e32 v108, v108
	v_rcp_f32_e32 v109, v109
	v_rcp_f32_e32 v98, v98
	v_rcp_f32_e32 v99, v99
	v_rcp_f32_e32 v100, v100
	v_rcp_f32_e32 v101, v101
	v_add_u32_e32 v250, 16, v252
	v_mad_i64_i32 v[250:251], s[0:1], v250, s56, v[248:249]
	v_pk_mul_f32 v[106:107], v[156:157], v[106:107] op_sel_hi:[0,1]
	v_pk_mul_f32 v[108:109], v[156:157], v[108:109] op_sel_hi:[0,1]
	v_pk_mul_f32 v[98:99], v[156:157], v[98:99] op_sel_hi:[0,1]
	v_pk_mul_f32 v[100:101], v[156:157], v[100:101] op_sel_hi:[0,1]
	v_pk_mul_f32 v[110:111], v[110:111], v[106:107]
	v_pk_mul_f32 v[112:113], v[112:113], v[108:109]
	v_pk_mul_f32 v[102:103], v[102:103], v[98:99]
	v_pk_mul_f32 v[104:105], v[104:105], v[100:101]
	v_cvt_pk_bf16_f32 v106, v110, v111
	v_cvt_pk_bf16_f32 v107, v112, v113
	v_cvt_pk_bf16_f32 v108, v102, v103
	v_cvt_pk_bf16_f32 v109, v104, v105
	global_store_dwordx4 v[250:251], v[106:109], off sc1
	s_waitcnt vmcnt(14)
	v_add_f32_e32 v154, v240, v241
	v_add_f32_e32 v155, v242, v243
	v_add_f32_e32 v154, v154, v155
	v_add_f32_e32 v155, v236, v237
	v_add_f32_e32 v182, v238, v239
	v_add_f32_e32 v155, v155, v182
	v_add_f32_e32 v154, v154, v155
	v_add_f32_e32 v155, v232, v233
	v_add_f32_e32 v182, v234, v235
	v_add_f32_e32 v155, v155, v182
	v_add_f32_e32 v154, v154, v155
	v_add_f32_e32 v155, v228, v229
	v_add_f32_e32 v182, v230, v231
	v_add_f32_e32 v155, v155, v182
	v_add_f32_e32 v154, v154, v155
	v_fmamk_f32 v154, v154, 0x3a800000, v184
	v_rsq_f32_e32 v154, v154
	global_load_dwordx4 v[228:231], v[246:247], off offset:2096
	global_load_dwordx4 v[232:235], v[246:247], off offset:2080
	global_load_dwordx4 v[236:239], v[246:247], off offset:2064
	global_load_dwordx4 v[240:243], v[246:247], off offset:2048
	v_pk_mul_f32 v[94:95], v[94:95], v[90:91]
	v_pk_mul_f32 v[96:97], v[96:97], v[92:93]
	v_mul_f32_e32 v158, 0xbfb8aa3b, v154
	v_mul_f32_e32 v156, v154, v154
	v_pk_mul_f32 v[86:87], v[86:87], v[82:83]
	v_pk_mul_f32 v[88:89], v[88:89], v[84:85]
	v_pk_mul_f32 v[90:91], v[90:91], v[158:159] op_sel_hi:[1,0]
	v_pk_mul_f32 v[92:93], v[92:93], v[158:159] op_sel_hi:[1,0]
	v_pk_mul_f32 v[82:83], v[82:83], v[158:159] op_sel_hi:[1,0]
	v_pk_mul_f32 v[84:85], v[84:85], v[158:159] op_sel_hi:[1,0]
	v_exp_f32_e32 v90, v90
	v_exp_f32_e32 v91, v91
	v_exp_f32_e32 v92, v92
	v_exp_f32_e32 v93, v93
	v_exp_f32_e32 v82, v82
	v_exp_f32_e32 v83, v83
	v_exp_f32_e32 v84, v84
	v_exp_f32_e32 v85, v85
	v_pk_add_f32 v[90:91], v[90:91], 1.0 op_sel_hi:[1,0]
	v_pk_add_f32 v[92:93], v[92:93], 1.0 op_sel_hi:[1,0]
	v_pk_add_f32 v[82:83], v[82:83], 1.0 op_sel_hi:[1,0]
	v_pk_add_f32 v[84:85], v[84:85], 1.0 op_sel_hi:[1,0]
	v_rcp_f32_e32 v90, v90
	v_rcp_f32_e32 v91, v91
	v_rcp_f32_e32 v92, v92
	v_rcp_f32_e32 v93, v93
	v_rcp_f32_e32 v82, v82
	v_rcp_f32_e32 v83, v83
	v_rcp_f32_e32 v84, v84
	v_rcp_f32_e32 v85, v85
	v_add_u32_e32 v250, 32, v252
	v_mad_i64_i32 v[250:251], s[0:1], v250, s56, v[248:249]
	v_pk_mul_f32 v[90:91], v[156:157], v[90:91] op_sel_hi:[0,1]
	v_pk_mul_f32 v[92:93], v[156:157], v[92:93] op_sel_hi:[0,1]
	v_pk_mul_f32 v[82:83], v[156:157], v[82:83] op_sel_hi:[0,1]
	v_pk_mul_f32 v[84:85], v[156:157], v[84:85] op_sel_hi:[0,1]
	v_pk_mul_f32 v[94:95], v[94:95], v[90:91]
	v_pk_mul_f32 v[96:97], v[96:97], v[92:93]
	v_pk_mul_f32 v[86:87], v[86:87], v[82:83]
	v_pk_mul_f32 v[88:89], v[88:89], v[84:85]
	v_cvt_pk_bf16_f32 v90, v94, v95
	v_cvt_pk_bf16_f32 v91, v96, v97
	v_cvt_pk_bf16_f32 v92, v86, v87
	v_cvt_pk_bf16_f32 v93, v88, v89
	global_store_dwordx4 v[250:251], v[90:93], off sc1
	s_waitcnt vmcnt(15)
	v_add_f32_e32 v154, v178, v179
	v_add_f32_e32 v155, v180, v181
	v_add_f32_e32 v154, v154, v155
	v_add_f32_e32 v155, v174, v175
	v_add_f32_e32 v182, v176, v177
	v_add_f32_e32 v155, v155, v182
	v_add_f32_e32 v154, v154, v155
	v_add_f32_e32 v155, v168, v169
	v_add_f32_e32 v182, v170, v171
	v_add_f32_e32 v155, v155, v182
	v_add_f32_e32 v154, v154, v155
	v_add_f32_e32 v155, v164, v165
	v_add_f32_e32 v182, v166, v167
	v_add_f32_e32 v155, v155, v182
	v_add_f32_e32 v154, v154, v155
	v_fmamk_f32 v154, v154, 0x3a800000, v184
	v_rsq_f32_e32 v154, v154
	global_load_dwordx4 v[164:167], v[246:247], off offset:3120
	global_load_dwordx4 v[168:171], v[246:247], off offset:3104
	global_load_dwordx4 v[174:177], v[246:247], off offset:3088
	global_load_dwordx4 v[178:181], v[246:247], off offset:3072
	v_pk_mul_f32 v[78:79], v[78:79], v[74:75]
	v_pk_mul_f32 v[80:81], v[80:81], v[76:77]
	v_mul_f32_e32 v158, 0xbfb8aa3b, v154
	v_mul_f32_e32 v156, v154, v154
	v_pk_mul_f32 v[70:71], v[70:71], v[66:67]
	v_pk_mul_f32 v[72:73], v[72:73], v[68:69]
	v_pk_mul_f32 v[74:75], v[74:75], v[158:159] op_sel_hi:[1,0]
	v_pk_mul_f32 v[76:77], v[76:77], v[158:159] op_sel_hi:[1,0]
	v_pk_mul_f32 v[66:67], v[66:67], v[158:159] op_sel_hi:[1,0]
	v_pk_mul_f32 v[68:69], v[68:69], v[158:159] op_sel_hi:[1,0]
	v_exp_f32_e32 v74, v74
	v_exp_f32_e32 v75, v75
	v_exp_f32_e32 v76, v76
	v_exp_f32_e32 v77, v77
	v_exp_f32_e32 v66, v66
	v_exp_f32_e32 v67, v67
	v_exp_f32_e32 v68, v68
	v_exp_f32_e32 v69, v69
	v_pk_add_f32 v[74:75], v[74:75], 1.0 op_sel_hi:[1,0]
	v_pk_add_f32 v[76:77], v[76:77], 1.0 op_sel_hi:[1,0]
	v_pk_add_f32 v[66:67], v[66:67], 1.0 op_sel_hi:[1,0]
	v_pk_add_f32 v[68:69], v[68:69], 1.0 op_sel_hi:[1,0]
	v_rcp_f32_e32 v74, v74
	v_rcp_f32_e32 v75, v75
	v_rcp_f32_e32 v76, v76
	v_rcp_f32_e32 v77, v77
	v_rcp_f32_e32 v66, v66
	v_rcp_f32_e32 v67, v67
	v_rcp_f32_e32 v68, v68
	v_rcp_f32_e32 v69, v69
	v_add_u32_e32 v250, 48, v252
	v_mad_i64_i32 v[250:251], s[0:1], v250, s56, v[248:249]
	v_pk_mul_f32 v[74:75], v[156:157], v[74:75] op_sel_hi:[0,1]
	v_pk_mul_f32 v[76:77], v[156:157], v[76:77] op_sel_hi:[0,1]
	v_pk_mul_f32 v[66:67], v[156:157], v[66:67] op_sel_hi:[0,1]
	v_pk_mul_f32 v[68:69], v[156:157], v[68:69] op_sel_hi:[0,1]
	v_pk_mul_f32 v[78:79], v[78:79], v[74:75]
	v_pk_mul_f32 v[80:81], v[80:81], v[76:77]
	v_pk_mul_f32 v[70:71], v[70:71], v[66:67]
	v_pk_mul_f32 v[72:73], v[72:73], v[68:69]
	v_cvt_pk_bf16_f32 v74, v78, v79
	v_cvt_pk_bf16_f32 v75, v80, v81
	v_cvt_pk_bf16_f32 v76, v70, v71
	v_cvt_pk_bf16_f32 v77, v72, v73
	global_store_dwordx4 v[250:251], v[74:77], off sc1
	s_waitcnt vmcnt(16)
	v_add_f32_e32 v154, v208, v209
	v_add_f32_e32 v155, v210, v211
	v_add_f32_e32 v154, v154, v155
	v_add_f32_e32 v155, v204, v205
	v_add_f32_e32 v182, v206, v207
	v_add_f32_e32 v155, v155, v182
	v_add_f32_e32 v154, v154, v155
	v_add_f32_e32 v155, v200, v201
	v_add_f32_e32 v182, v202, v203
	v_add_f32_e32 v155, v155, v182
	v_add_f32_e32 v154, v154, v155
	v_add_f32_e32 v155, v196, v197
	v_add_f32_e32 v182, v198, v199
	v_add_f32_e32 v155, v155, v182
	v_add_f32_e32 v154, v154, v155
	v_fmamk_f32 v154, v154, 0x3a800000, v184
	v_rsq_f32_e32 v154, v154
	v_pk_mul_f32 v[62:63], v[62:63], v[58:59]
	v_pk_mul_f32 v[64:65], v[64:65], v[60:61]
	v_mul_f32_e32 v158, 0xbfb8aa3b, v154
	v_mul_f32_e32 v156, v154, v154
	v_pk_mul_f32 v[54:55], v[54:55], v[50:51]
	v_pk_mul_f32 v[56:57], v[56:57], v[52:53]
	v_pk_mul_f32 v[58:59], v[58:59], v[158:159] op_sel_hi:[1,0]
	v_pk_mul_f32 v[60:61], v[60:61], v[158:159] op_sel_hi:[1,0]
	v_pk_mul_f32 v[50:51], v[50:51], v[158:159] op_sel_hi:[1,0]
	v_pk_mul_f32 v[52:53], v[52:53], v[158:159] op_sel_hi:[1,0]
	v_exp_f32_e32 v58, v58
	v_exp_f32_e32 v59, v59
	v_exp_f32_e32 v60, v60
	v_exp_f32_e32 v61, v61
	v_exp_f32_e32 v50, v50
	v_exp_f32_e32 v51, v51
	v_exp_f32_e32 v52, v52
	v_exp_f32_e32 v53, v53
	v_pk_add_f32 v[58:59], v[58:59], 1.0 op_sel_hi:[1,0]
	v_pk_add_f32 v[60:61], v[60:61], 1.0 op_sel_hi:[1,0]
	v_pk_add_f32 v[50:51], v[50:51], 1.0 op_sel_hi:[1,0]
	v_pk_add_f32 v[52:53], v[52:53], 1.0 op_sel_hi:[1,0]
	v_rcp_f32_e32 v58, v58
	v_rcp_f32_e32 v59, v59
	v_rcp_f32_e32 v60, v60
	v_rcp_f32_e32 v61, v61
	v_rcp_f32_e32 v50, v50
	v_rcp_f32_e32 v51, v51
	v_rcp_f32_e32 v52, v52
	v_rcp_f32_e32 v53, v53
	v_add_u32_e32 v250, 128, v252
	v_mad_i64_i32 v[250:251], s[0:1], v250, s56, v[248:249]
	v_pk_mul_f32 v[58:59], v[156:157], v[58:59] op_sel_hi:[0,1]
	v_pk_mul_f32 v[60:61], v[156:157], v[60:61] op_sel_hi:[0,1]
	v_pk_mul_f32 v[50:51], v[156:157], v[50:51] op_sel_hi:[0,1]
	v_pk_mul_f32 v[52:53], v[156:157], v[52:53] op_sel_hi:[0,1]
	v_pk_mul_f32 v[62:63], v[62:63], v[58:59]
	v_pk_mul_f32 v[64:65], v[64:65], v[60:61]
	v_pk_mul_f32 v[54:55], v[54:55], v[50:51]
	v_pk_mul_f32 v[56:57], v[56:57], v[52:53]
	v_cvt_pk_bf16_f32 v58, v62, v63
	v_cvt_pk_bf16_f32 v59, v64, v65
	v_cvt_pk_bf16_f32 v60, v54, v55
	v_cvt_pk_bf16_f32 v61, v56, v57
	global_store_dwordx4 v[250:251], v[58:61], off sc1
	s_waitcnt vmcnt(12)
	v_add_f32_e32 v154, v224, v225
	v_add_f32_e32 v155, v226, v227
	v_add_f32_e32 v154, v154, v155
	v_add_f32_e32 v155, v220, v221
	v_add_f32_e32 v182, v222, v223
	v_add_f32_e32 v155, v155, v182
	v_add_f32_e32 v154, v154, v155
	v_add_f32_e32 v155, v216, v217
	v_add_f32_e32 v182, v218, v219
	v_add_f32_e32 v155, v155, v182
	v_add_f32_e32 v154, v154, v155
	v_add_f32_e32 v155, v212, v213
	v_add_f32_e32 v182, v214, v215
	v_add_f32_e32 v155, v155, v182
	v_add_f32_e32 v154, v154, v155
	v_fmamk_f32 v154, v154, 0x3a800000, v184
	v_rsq_f32_e32 v154, v154
	v_pk_mul_f32 v[46:47], v[46:47], v[42:43]
	v_pk_mul_f32 v[48:49], v[48:49], v[44:45]
	v_mul_f32_e32 v158, 0xbfb8aa3b, v154
	v_mul_f32_e32 v156, v154, v154
	v_pk_mul_f32 v[38:39], v[38:39], v[34:35]
	v_pk_mul_f32 v[40:41], v[40:41], v[36:37]
	v_pk_mul_f32 v[42:43], v[42:43], v[158:159] op_sel_hi:[1,0]
	v_pk_mul_f32 v[44:45], v[44:45], v[158:159] op_sel_hi:[1,0]
	v_pk_mul_f32 v[34:35], v[34:35], v[158:159] op_sel_hi:[1,0]
	v_pk_mul_f32 v[36:37], v[36:37], v[158:159] op_sel_hi:[1,0]
	v_exp_f32_e32 v42, v42
	v_exp_f32_e32 v43, v43
	v_exp_f32_e32 v44, v44
	v_exp_f32_e32 v45, v45
	v_exp_f32_e32 v34, v34
	v_exp_f32_e32 v35, v35
	v_exp_f32_e32 v36, v36
	v_exp_f32_e32 v37, v37
	v_pk_add_f32 v[42:43], v[42:43], 1.0 op_sel_hi:[1,0]
	v_pk_add_f32 v[44:45], v[44:45], 1.0 op_sel_hi:[1,0]
	v_pk_add_f32 v[34:35], v[34:35], 1.0 op_sel_hi:[1,0]
	v_pk_add_f32 v[36:37], v[36:37], 1.0 op_sel_hi:[1,0]
	v_rcp_f32_e32 v42, v42
	v_rcp_f32_e32 v43, v43
	v_rcp_f32_e32 v44, v44
	v_rcp_f32_e32 v45, v45
	v_rcp_f32_e32 v34, v34
	v_rcp_f32_e32 v35, v35
	v_rcp_f32_e32 v36, v36
	v_rcp_f32_e32 v37, v37
	v_add_u32_e32 v250, 144, v252
	v_mad_i64_i32 v[250:251], s[0:1], v250, s56, v[248:249]
	v_pk_mul_f32 v[42:43], v[156:157], v[42:43] op_sel_hi:[0,1]
	v_pk_mul_f32 v[44:45], v[156:157], v[44:45] op_sel_hi:[0,1]
	v_pk_mul_f32 v[34:35], v[156:157], v[34:35] op_sel_hi:[0,1]
	v_pk_mul_f32 v[36:37], v[156:157], v[36:37] op_sel_hi:[0,1]
	v_pk_mul_f32 v[46:47], v[46:47], v[42:43]
	v_pk_mul_f32 v[48:49], v[48:49], v[44:45]
	v_pk_mul_f32 v[38:39], v[38:39], v[34:35]
	v_pk_mul_f32 v[40:41], v[40:41], v[36:37]
	v_cvt_pk_bf16_f32 v42, v46, v47
	v_cvt_pk_bf16_f32 v43, v48, v49
	v_cvt_pk_bf16_f32 v44, v38, v39
	v_cvt_pk_bf16_f32 v45, v40, v41
	global_store_dwordx4 v[250:251], v[42:45], off sc1
	s_waitcnt vmcnt(8)
	v_add_f32_e32 v154, v240, v241
	v_add_f32_e32 v155, v242, v243
	v_add_f32_e32 v154, v154, v155
	v_add_f32_e32 v155, v236, v237
	v_add_f32_e32 v182, v238, v239
	v_add_f32_e32 v155, v155, v182
	v_add_f32_e32 v154, v154, v155
	v_add_f32_e32 v155, v232, v233
	v_add_f32_e32 v182, v234, v235
	v_add_f32_e32 v155, v155, v182
	v_add_f32_e32 v154, v154, v155
	v_add_f32_e32 v155, v228, v229
	v_add_f32_e32 v182, v230, v231
	v_add_f32_e32 v155, v155, v182
	v_add_f32_e32 v154, v154, v155
	v_fmamk_f32 v154, v154, 0x3a800000, v184
	v_rsq_f32_e32 v154, v154
	v_pk_mul_f32 v[30:31], v[30:31], v[26:27]
	v_pk_mul_f32 v[32:33], v[32:33], v[28:29]
	v_mul_f32_e32 v158, 0xbfb8aa3b, v154
	v_mul_f32_e32 v156, v154, v154
	v_pk_mul_f32 v[22:23], v[22:23], v[18:19]
	v_pk_mul_f32 v[24:25], v[24:25], v[20:21]
	v_pk_mul_f32 v[26:27], v[26:27], v[158:159] op_sel_hi:[1,0]
	v_pk_mul_f32 v[28:29], v[28:29], v[158:159] op_sel_hi:[1,0]
	v_pk_mul_f32 v[18:19], v[18:19], v[158:159] op_sel_hi:[1,0]
	v_pk_mul_f32 v[20:21], v[20:21], v[158:159] op_sel_hi:[1,0]
	v_exp_f32_e32 v26, v26
	v_exp_f32_e32 v27, v27
	v_exp_f32_e32 v28, v28
	v_exp_f32_e32 v29, v29
	v_exp_f32_e32 v18, v18
	v_exp_f32_e32 v19, v19
	v_exp_f32_e32 v20, v20
	v_exp_f32_e32 v21, v21
	v_pk_add_f32 v[26:27], v[26:27], 1.0 op_sel_hi:[1,0]
	v_pk_add_f32 v[28:29], v[28:29], 1.0 op_sel_hi:[1,0]
	v_pk_add_f32 v[18:19], v[18:19], 1.0 op_sel_hi:[1,0]
	v_pk_add_f32 v[20:21], v[20:21], 1.0 op_sel_hi:[1,0]
	v_rcp_f32_e32 v26, v26
	v_rcp_f32_e32 v27, v27
	v_rcp_f32_e32 v28, v28
	v_rcp_f32_e32 v29, v29
	v_rcp_f32_e32 v18, v18
	v_rcp_f32_e32 v19, v19
	v_rcp_f32_e32 v20, v20
	v_rcp_f32_e32 v21, v21
	v_add_u32_e32 v250, 160, v252
	v_mad_i64_i32 v[250:251], s[0:1], v250, s56, v[248:249]
	v_pk_mul_f32 v[26:27], v[156:157], v[26:27] op_sel_hi:[0,1]
	v_pk_mul_f32 v[28:29], v[156:157], v[28:29] op_sel_hi:[0,1]
	v_pk_mul_f32 v[18:19], v[156:157], v[18:19] op_sel_hi:[0,1]
	v_pk_mul_f32 v[20:21], v[156:157], v[20:21] op_sel_hi:[0,1]
	v_pk_mul_f32 v[30:31], v[30:31], v[26:27]
	v_pk_mul_f32 v[32:33], v[32:33], v[28:29]
	v_pk_mul_f32 v[22:23], v[22:23], v[18:19]
	v_pk_mul_f32 v[24:25], v[24:25], v[20:21]
	v_cvt_pk_bf16_f32 v26, v30, v31
	v_cvt_pk_bf16_f32 v27, v32, v33
	v_cvt_pk_bf16_f32 v28, v22, v23
	v_cvt_pk_bf16_f32 v29, v24, v25
	global_store_dwordx4 v[250:251], v[26:29], off sc1
	s_waitcnt vmcnt(4)
	v_add_f32_e32 v154, v178, v179
	v_add_f32_e32 v155, v180, v181
	v_add_f32_e32 v154, v154, v155
	v_add_f32_e32 v155, v174, v175
	v_add_f32_e32 v182, v176, v177
	v_add_f32_e32 v155, v155, v182
	v_add_f32_e32 v154, v154, v155
	v_add_f32_e32 v155, v168, v169
	v_add_f32_e32 v182, v170, v171
	v_add_f32_e32 v155, v155, v182
	v_add_f32_e32 v154, v154, v155
	v_add_f32_e32 v155, v164, v165
	v_add_f32_e32 v182, v166, v167
	v_add_f32_e32 v155, v155, v182
	v_add_f32_e32 v154, v154, v155
	v_fmamk_f32 v154, v154, 0x3a800000, v184
	v_rsq_f32_e32 v154, v154
	v_pk_mul_f32 v[14:15], v[14:15], v[10:11]
	v_pk_mul_f32 v[16:17], v[16:17], v[12:13]
	v_mul_f32_e32 v158, 0xbfb8aa3b, v154
	v_mul_f32_e32 v156, v154, v154
	v_pk_mul_f32 v[2:3], v[2:3], v[6:7]
	v_pk_mul_f32 v[4:5], v[4:5], v[8:9]
	v_pk_mul_f32 v[10:11], v[10:11], v[158:159] op_sel_hi:[1,0]
	v_pk_mul_f32 v[12:13], v[12:13], v[158:159] op_sel_hi:[1,0]
	v_pk_mul_f32 v[6:7], v[6:7], v[158:159] op_sel_hi:[1,0]
	v_pk_mul_f32 v[8:9], v[8:9], v[158:159] op_sel_hi:[1,0]
	v_exp_f32_e32 v10, v10
	v_exp_f32_e32 v11, v11
	v_exp_f32_e32 v12, v12
	v_exp_f32_e32 v13, v13
	v_exp_f32_e32 v6, v6
	v_exp_f32_e32 v7, v7
	v_exp_f32_e32 v8, v8
	v_exp_f32_e32 v9, v9
	v_pk_add_f32 v[10:11], v[10:11], 1.0 op_sel_hi:[1,0]
	v_pk_add_f32 v[12:13], v[12:13], 1.0 op_sel_hi:[1,0]
	v_pk_add_f32 v[6:7], v[6:7], 1.0 op_sel_hi:[1,0]
	v_pk_add_f32 v[8:9], v[8:9], 1.0 op_sel_hi:[1,0]
	v_rcp_f32_e32 v10, v10
	v_rcp_f32_e32 v11, v11
	v_rcp_f32_e32 v12, v12
	v_rcp_f32_e32 v13, v13
	v_rcp_f32_e32 v6, v6
	v_rcp_f32_e32 v7, v7
	v_rcp_f32_e32 v8, v8
	v_rcp_f32_e32 v9, v9
	v_add_u32_e32 v250, 176, v252
	v_mad_i64_i32 v[250:251], s[0:1], v250, s56, v[248:249]
	v_pk_mul_f32 v[10:11], v[156:157], v[10:11] op_sel_hi:[0,1]
	v_pk_mul_f32 v[12:13], v[156:157], v[12:13] op_sel_hi:[0,1]
	v_pk_mul_f32 v[6:7], v[156:157], v[6:7] op_sel_hi:[0,1]
	v_pk_mul_f32 v[8:9], v[156:157], v[8:9] op_sel_hi:[0,1]
	v_pk_mul_f32 v[14:15], v[14:15], v[10:11]
	v_pk_mul_f32 v[16:17], v[16:17], v[12:13]
	v_pk_mul_f32 v[2:3], v[2:3], v[6:7]
	v_pk_mul_f32 v[4:5], v[4:5], v[8:9]
	v_cvt_pk_bf16_f32 v10, v14, v15
	v_cvt_pk_bf16_f32 v11, v16, v17
	v_cvt_pk_bf16_f32 v12, v2, v3
	v_cvt_pk_bf16_f32 v13, v4, v5
	global_store_dwordx4 v[250:251], v[10:13], off sc1
	s_and_b64 vcc, exec, s[2:3]
	s_mov_b64 s[0:1], -1
	s_cbranch_vccnz .LBB0_1641
	s_andn2_b64 vcc, exec, s[10:11]
	s_cbranch_vccnz .LBB0_1640
	s_barrier
	s_branch .LBB0_1640

.LBB0_1657:
	v_readlane_b32 s50, v254, 38
	s_add_i32 s50, s50, 1
	s_waitcnt lgkmcnt(0)
	s_cmp_ge_i32 s50, s63
	s_cbranch_scc1 .LBB0_1669
	s_waitcnt vmcnt(0)
	v_mov_b32_e32 v0, v173
	s_waitcnt vmcnt(0)
	s_barrier
	s_nop 0
	v_cmp_eq_u32_e32 vcc, 0, v0
	s_and_saveexec_b64 s[0:1], vcc
	v_readlane_b32 s47, v254, 37
	s_cbranch_execz .LBB0_1711
	s_cmp_eq_u32 s69, 0x100
	s_cbranch_scc0 .Lgb_global
	s_cmp_eq_u32 s62, 0
	s_cbranch_scc0 .Lgb_global
	s_add_i32 s2, s50, -2
	s_cmp_lt_u32 s2, 32
	s_cbranch_scc0 .Lgb_global
	s_and_b32 s3, s2, 7
	s_lshr_b32 s4, s2, 3
	s_mov_b32 s8, 1
	s_cmp_eq_u32 s3, 0
	s_cbranch_scc1 .Lgb_go
	s_mov_b32 s8, 2
	s_cmp_eq_u32 s3, 5
	s_cbranch_scc1 .Lgb_go
	s_mov_b32 s8, 3
	s_cmp_eq_u32 s3, 6
	s_cbranch_scc1 .Lgb_go
	s_mov_b32 s8, 4
	s_cmp_eq_u32 s3, 7
	s_cbranch_scc0 .Lgb_global
	s_cmp_lt_u32 s4, 3
	s_cbranch_scc0 .Lgb_global
.Lgb_go:
	s_lshl_b32 s4, s4, 2
	s_add_i32 s8, s8, s4
	s_lshl_b32 s8, s8, 2
	v_readlane_b32 s5, v254, 0
	s_nop 0
	s_and_b32 s6, s5, 7
	s_lshl_b32 s6, s6, 3
	s_bfe_u32 s7, s5, 0x30003
	s_or_b32 s6, s6, s7
	s_lshl_b32 s6, s6, 8
	s_add_i32 s6, s6, 0xd680080
	s_add_u32 s6, s64, s6
	s_addc_u32 s7, s65, 0
	s_waitcnt vmcnt(0) lgkmcnt(0)
	s_waitcnt vmcnt(0)
	global_atomic_add v0, v1, v188, s[6:7] sc0
	s_mov_b32 s9, 0
	s_waitcnt vmcnt(0)
	v_add_u32_e32 v0, 1, v0
	v_cmp_le_u32_e32 vcc, s8, v0
	s_cbranch_vccnz .Lgb_acq
.Lgb_poll:
	s_sleep 1
	global_load_dword v0, v1, s[6:7] sc1
	s_waitcnt vmcnt(0)
	v_cmp_le_u32_e32 vcc, s8, v0
	s_cbranch_vccnz .Lgb_acq
	s_add_i32 s9, s9, 1
	s_cmp_lt_u32 s9, 0x400000
	s_cbranch_scc1 .Lgb_poll
.Lgb_acq:
	buffer_inv sc1
	s_waitcnt vmcnt(0)
	s_branch .LBB0_1711
.Lgb_global:
	v_mov_b32_e32 v0, s57
	s_getreg_b32 s2, hwreg(HW_REG_XCC_ID, 0, 4)
	s_waitcnt vmcnt(0) expcnt(0) lgkmcnt(0)
	ds_read_b32 v3, v0
	v_mov_b32_e32 v0, s58
	ds_read_b32 v0, v0
	s_and_b32 s33, s2, 15
	s_waitcnt lgkmcnt(1)
	v_cmp_ne_u32_e32 vcc, 0, v3
	s_cbranch_vccnz .LBB0_1675
	s_add_u32 s2, s64, 0xd680200
	s_addc_u32 s3, s65, 0
	s_add_u32 s4, s64, 0xd680400
	s_addc_u32 s5, s65, 0
	s_add_u32 s6, s64, 0xd680500
	s_addc_u32 s7, s65, 0
	s_add_u32 s8, s64, 0xd680600
	s_addc_u32 s9, s65, 0
	s_add_u32 s10, s64, 0xd680700
	s_addc_u32 s11, s65, 0
	s_add_u32 s12, s64, 0xd680800
	s_addc_u32 s13, s65, 0
	s_add_u32 s14, s64, 0xd680900
	s_addc_u32 s15, s65, 0
	s_add_u32 s16, s64, 0xd680a00
	s_addc_u32 s17, s65, 0
	s_add_u32 s18, s64, 0xd680b00
	s_addc_u32 s19, s65, 0
	s_add_u32 s20, s64, 0xd680c00
	s_addc_u32 s21, s65, 0
	s_add_u32 s22, s64, 0xd680d00
	s_addc_u32 s23, s65, 0
	s_add_u32 s24, s64, 0xd680e00
	s_addc_u32 s25, s65, 0
	s_add_u32 s26, s64, 0xd680f00
	s_addc_u32 s27, s65, 0
	s_add_u32 s28, s64, 0xd681000
	s_addc_u32 s29, s65, 0
	s_add_u32 s30, s64, 0xd681100
	s_addc_u32 s31, s65, 0
	s_add_u32 s34, s64, 0xd681200
	s_addc_u32 s35, s65, 0
	s_add_u32 s36, s64, 0xd681300
	s_mov_b32 s44, s69
	s_addc_u32 s37, s65, 0
	s_mov_b32 s46, 1
	s_branch .LBB0_1662
